# IN and Q GEMM epilogues: second-half column-vector loads hoisted into the first load batch (no store-drain wait mid-epilogue)
# baseline (speedup 1.0000x reference)
; __device__ __forceinline__ u32x4 pack8(const f32x4 v0, const f32x4 v1) { u32x4 w; w.x = cvt_pk_bf16(v0[0], v0[1]); w.y = cvt_pk_bf16(v0[2], v0[3]); w.z = cvt_pk_bf16(v1[0], v1[1]); w.w = cvt_pk_bf16(v1[2], v1[3]); return w; }
; __device__ __forceinline__ void row_stats8(const float* MUR, int row0, float (&mu)[2][4], float (&rs)[2][4]) {
; #pragma unroll
;     for (int ai = 0; ai < 2; ++ai)
; #pragma unroll
;         for (int m = 0; m < 4; ++m) { const f32x2 t = *(const f32x2*)(MUR + 2 * (size_t)(row0 + ai * HALF + m * 16)); mu[ai][m] = t.x; rs[ai][m] = t.y; }
; }
;     __device__ __forceinline__ void operator()(const f32x4 (&acc)[2][2][4][2], const Unit& u, int wr, int wc, int fr, int fq) const {
;         const int row0 = u.pm * BM + wr * 64 + fr, col0 = u.pn * BM + wc * 32 + 8 * fq;
;         float mu[2][4], rs[2][4]; row_stats8(MUR, row0, mu, rs);
; #pragma unroll
;         for (int bj = 0; bj < 2; ++bj) { const f32x4 s0 = *(const f32x4*)(cs + col0 + bj * HALF), s1 = *(const f32x4*)(cs + col0 + bj * HALF + 4), b0 = *(const f32x4*)(cb + col0 + bj * HALF), b1 = *(const f32x4*)(cb + col0 + bj * HALF + 4);
; #pragma unroll
;             for (int ai = 0; ai < 2; ++ai)
; #pragma unroll
;                 for (int m = 0; m < 4; ++m) { const f32x4 v0 = (acc[ai][bj][m][0] - s0 * mu[ai][m]) * rs[ai][m] + b0, v1 = (acc[ai][bj][m][1] - s1 * mu[ai][m]) * rs[ai][m] + b1;
;                     *(u32x4*)(O + (size_t)(row0 + ai * HALF + m * 16) * ldc + col0 + bj * HALF) = pack8(v0, v1); } }
.LBB0_119:
	v_lshl_add_u32 v158, s7, 8, v171
	v_lshl_or_b32 v174, s6, 8, v197
	v_ashrrev_i32_e32 v175, 31, v174
	v_readlane_b32 s6, v254, 14
	v_or_b32_e32 v176, 16, v158
	v_ashrrev_i32_e32 v159, 31, v158
	v_lshlrev_b64 v[136:137], 2, v[174:175]
	v_readlane_b32 s7, v254, 15
	v_ashrrev_i32_e32 v177, 31, v176
	v_or_b32_e32 v186, 32, v158
	v_lshl_add_u64 v[128:129], v[158:159], 3, s[88:89]
	v_lshl_add_u64 v[180:181], s[6:7], 0, v[136:137]
	v_lshl_add_u64 v[138:139], v[176:177], 3, s[88:89]
	v_ashrrev_i32_e32 v187, 31, v186
	v_readlane_b32 s6, v254, 18
	global_load_dwordx2 v[160:161], v[128:129], off
	s_nop 0
	global_load_dwordx4 v[128:131], v[180:181], off offset:16
	global_load_dwordx4 v[132:135], v[180:181], off
	global_load_dwordx2 v[178:179], v[138:139], off
	v_lshl_add_u64 v[138:139], v[186:187], 3, s[88:89]
	v_readlane_b32 s7, v254, 19
	v_or_b32_e32 v200, 48, v158
	global_load_dwordx2 v[162:163], v[138:139], off
	v_lshl_add_u64 v[182:183], s[6:7], 0, v[136:137]
	v_ashrrev_i32_e32 v201, 31, v200
	global_load_dwordx4 v[140:143], v[182:183], off
	global_load_dwordx4 v[136:139], v[182:183], off offset:16
	global_load_dwordx4 v[210:213], v[180:181], off offset:512
	global_load_dwordx4 v[214:217], v[182:183], off offset:512
	global_load_dwordx4 v[218:221], v[180:181], off offset:528
	global_load_dwordx2 v[222:223], v[182:183], off offset:528
	global_load_dwordx2 v[234:235], v[182:183], off offset:536
	v_lshl_add_u64 v[154:155], v[200:201], 3, s[88:89]
	v_add_u32_e32 v194, 0x90, v158
	global_load_dwordx2 v[156:157], v[154:155], off
	v_add_u32_e32 v202, 0x80, v158
	v_ashrrev_i32_e32 v195, 31, v194
	v_ashrrev_i32_e32 v203, 31, v202
	v_lshlrev_b64 v[190:191], 1, v[174:175]
	v_lshl_add_u64 v[174:175], v[194:195], 3, s[88:89]
	global_load_dwordx2 v[174:175], v[174:175], off
	v_lshl_add_u64 v[154:155], v[202:203], 3, s[88:89]
	global_load_dwordx2 v[154:155], v[154:155], off
	v_add_u32_e32 v188, 0xa0, v158
	v_add_u32_e32 v184, 0xb0, v158
	v_ashrrev_i32_e32 v189, 31, v188
	v_readlane_b32 s6, v252, 36
	v_ashrrev_i32_e32 v185, 31, v184
	v_lshlrev_b64 v[158:159], 11, v[158:159]
	v_lshl_add_u64 v[192:193], v[188:189], 3, s[88:89]
	v_readlane_b32 s7, v252, 37
	v_lshl_add_u64 v[204:205], v[184:185], 3, s[88:89]
	v_lshlrev_b64 v[208:209], 11, v[176:177]
	v_lshl_add_u64 v[206:207], s[6:7], 0, v[158:159]
	global_load_dwordx2 v[176:177], v[192:193], off
	global_load_dwordx2 v[158:159], v[204:205], off
	v_lshlrev_b64 v[186:187], 11, v[186:187]
	v_lshl_add_u64 v[204:205], v[206:207], 0, v[190:191]
	v_lshl_add_u64 v[192:193], s[6:7], 0, v[208:209]
	v_lshl_add_u64 v[186:187], s[6:7], 0, v[186:187]
	v_lshl_add_u64 v[192:193], v[192:193], 0, v[190:191]
	v_lshl_add_u64 v[186:187], v[186:187], 0, v[190:191]
	s_andn2_b64 vcc, exec, s[8:9]
	s_waitcnt vmcnt(0)
	v_pk_fma_f32 v[120:121], v[160:161], v[128:129], v[120:121] op_sel_hi:[0,1,1] neg_lo:[1,0,0] neg_hi:[1,0,0]
	v_pk_fma_f32 v[124:125], v[160:161], v[132:133], v[124:125] op_sel_hi:[0,1,1] neg_lo:[1,0,0] neg_hi:[1,0,0]
	v_pk_fma_f32 v[126:127], v[160:161], v[134:135], v[126:127] op_sel_hi:[0,1,1] neg_lo:[1,0,0] neg_hi:[1,0,0]
	v_pk_fma_f32 v[122:123], v[160:161], v[130:131], v[122:123] op_sel_hi:[0,1,1] neg_lo:[1,0,0] neg_hi:[1,0,0]
	v_pk_fma_f32 v[116:117], v[178:179], v[132:133], v[116:117] op_sel_hi:[0,1,1] neg_lo:[1,0,0] neg_hi:[1,0,0]
	v_pk_fma_f32 v[118:119], v[178:179], v[134:135], v[118:119] op_sel_hi:[0,1,1] neg_lo:[1,0,0] neg_hi:[1,0,0]
	v_pk_fma_f32 v[104:105], v[162:163], v[128:129], v[104:105] op_sel_hi:[0,1,1] neg_lo:[1,0,0] neg_hi:[1,0,0]
	v_pk_fma_f32 v[106:107], v[162:163], v[130:131], v[106:107] op_sel_hi:[0,1,1] neg_lo:[1,0,0] neg_hi:[1,0,0]
	v_pk_fma_f32 v[126:127], v[160:161], v[126:127], v[142:143] op_sel:[1,0,0]
	v_pk_fma_f32 v[124:125], v[160:161], v[124:125], v[140:141] op_sel:[1,0,0]
	v_pk_fma_f32 v[208:209], v[162:163], v[104:105], v[136:137] op_sel:[1,0,0]
	v_cvt_pk_bf16_f32 v104, v124, v125
	v_cvt_pk_bf16_f32 v105, v126, v127
	v_pk_fma_f32 v[112:113], v[178:179], v[128:129], v[112:113] op_sel_hi:[0,1,1] neg_lo:[1,0,0] neg_hi:[1,0,0]
	v_pk_fma_f32 v[114:115], v[178:179], v[130:131], v[114:115] op_sel_hi:[0,1,1] neg_lo:[1,0,0] neg_hi:[1,0,0]
	v_pk_fma_f32 v[108:109], v[162:163], v[132:133], v[108:109] op_sel_hi:[0,1,1] neg_lo:[1,0,0] neg_hi:[1,0,0]
	v_pk_fma_f32 v[110:111], v[162:163], v[134:135], v[110:111] op_sel_hi:[0,1,1] neg_lo:[1,0,0] neg_hi:[1,0,0]
	v_pk_fma_f32 v[122:123], v[160:161], v[122:123], v[138:139] op_sel:[1,0,0]
	v_pk_fma_f32 v[120:121], v[160:161], v[120:121], v[136:137] op_sel:[1,0,0]
	v_pk_fma_f32 v[118:119], v[178:179], v[118:119], v[142:143] op_sel:[1,0,0]
	v_pk_fma_f32 v[116:117], v[178:179], v[116:117], v[140:141] op_sel:[1,0,0]
	v_pk_fma_f32 v[206:207], v[162:163], v[106:107], v[138:139] op_sel:[1,0,0]
	v_cvt_pk_bf16_f32 v106, v120, v121
	v_cvt_pk_bf16_f32 v107, v122, v123
	global_store_dwordx4 v[204:205], v[104:107], off
	v_pk_fma_f32 v[100:101], v[156:157], v[132:133], v[100:101] op_sel_hi:[0,1,1] neg_lo:[1,0,0] neg_hi:[1,0,0]
	v_pk_fma_f32 v[96:97], v[156:157], v[128:129], v[96:97] op_sel_hi:[0,1,1] neg_lo:[1,0,0] neg_hi:[1,0,0]
	v_cvt_pk_bf16_f32 v104, v116, v117
	v_cvt_pk_bf16_f32 v105, v118, v119
	v_pk_fma_f32 v[114:115], v[178:179], v[114:115], v[138:139] op_sel:[1,0,0]
	v_pk_fma_f32 v[112:113], v[178:179], v[112:113], v[136:137] op_sel:[1,0,0]
	v_pk_fma_f32 v[110:111], v[162:163], v[110:111], v[142:143] op_sel:[1,0,0]
	v_pk_fma_f32 v[108:109], v[162:163], v[108:109], v[140:141] op_sel:[1,0,0]
	v_cvt_pk_bf16_f32 v106, v112, v113
	v_cvt_pk_bf16_f32 v107, v114, v115
	global_store_dwordx4 v[192:193], v[104:107], off
; __device__ __forceinline__ u32x4 pack8(const f32x4 v0, const f32x4 v1) { u32x4 w; w.x = cvt_pk_bf16(v0[0], v0[1]); w.y = cvt_pk_bf16(v0[2], v0[3]); w.z = cvt_pk_bf16(v1[0], v1[1]); w.w = cvt_pk_bf16(v1[2], v1[3]); return w; }
;     __device__ __forceinline__ void operator()(const f32x4 (&acc)[2][2][4][2], const Unit& u, int wr, int wc, int fr, int fq) const {
;     ...
;         for (int bj = 0; bj < 2; ++bj) { const f32x4 s0 = *(const f32x4*)(cs + col0 + bj * HALF), s1 = *(const f32x4*)(cs + col0 + bj * HALF + 4), b0 = *(const f32x4*)(cb + col0 + bj * HALF), b1 = *(const f32x4*)(cb + col0 + bj * HALF + 4);
; #pragma unroll
;             for (int ai = 0; ai < 2; ++ai)
; #pragma unroll
;                 for (int m = 0; m < 4; ++m) { const f32x4 v0 = (acc[ai][bj][m][0] - s0 * mu[ai][m]) * rs[ai][m] + b0, v1 = (acc[ai][bj][m][1] - s1 * mu[ai][m]) * rs[ai][m] + b1;
;                     *(u32x4*)(O + (size_t)(row0 + ai * HALF + m * 16) * ldc + col0 + bj * HALF) = pack8(v0, v1); } }
	v_pk_fma_f32 v[102:103], v[156:157], v[134:135], v[102:103] op_sel_hi:[0,1,1] neg_lo:[1,0,0] neg_hi:[1,0,0]
	v_pk_fma_f32 v[100:101], v[156:157], v[100:101], v[140:141] op_sel:[1,0,0]
	v_cvt_pk_bf16_f32 v104, v108, v109
	v_cvt_pk_bf16_f32 v105, v110, v111
	v_pk_fma_f32 v[98:99], v[156:157], v[130:131], v[98:99] op_sel_hi:[0,1,1] neg_lo:[1,0,0] neg_hi:[1,0,0]
	v_pk_fma_f32 v[96:97], v[156:157], v[96:97], v[136:137] op_sel:[1,0,0]
	v_cvt_pk_bf16_f32 v106, v208, v209
	v_cvt_pk_bf16_f32 v107, v206, v207
	global_store_dwordx4 v[186:187], v[104:107], off
	v_pk_fma_f32 v[102:103], v[156:157], v[102:103], v[142:143] op_sel:[1,0,0]
	v_pk_fma_f32 v[92:93], v[154:155], v[132:133], v[92:93] op_sel_hi:[0,1,1] neg_lo:[1,0,0] neg_hi:[1,0,0]
	v_pk_fma_f32 v[104:105], v[156:157], v[98:99], v[138:139] op_sel:[1,0,0]
	v_cvt_pk_bf16_f32 v98, v100, v101
	v_cvt_pk_bf16_f32 v99, v102, v103
	v_cvt_pk_bf16_f32 v100, v96, v97
	v_lshlrev_b64 v[96:97], 11, v[200:201]
	v_lshl_add_u64 v[96:97], s[6:7], 0, v[96:97]
	v_pk_fma_f32 v[88:89], v[154:155], v[128:129], v[88:89] op_sel_hi:[0,1,1] neg_lo:[1,0,0] neg_hi:[1,0,0]
	v_lshl_add_u64 v[96:97], v[96:97], 0, v[190:191]
	v_pk_fma_f32 v[94:95], v[154:155], v[134:135], v[94:95] op_sel_hi:[0,1,1] neg_lo:[1,0,0] neg_hi:[1,0,0]
	v_pk_fma_f32 v[92:93], v[154:155], v[92:93], v[140:141] op_sel:[1,0,0]
	v_pk_fma_f32 v[90:91], v[154:155], v[130:131], v[90:91] op_sel_hi:[0,1,1] neg_lo:[1,0,0] neg_hi:[1,0,0]
	v_pk_fma_f32 v[88:89], v[154:155], v[88:89], v[136:137] op_sel:[1,0,0]
	v_cvt_pk_bf16_f32 v101, v104, v105
	global_store_dwordx4 v[96:97], v[98:101], off
	v_pk_fma_f32 v[94:95], v[154:155], v[94:95], v[142:143] op_sel:[1,0,0]
	v_pk_fma_f32 v[84:85], v[174:175], v[132:133], v[84:85] op_sel_hi:[0,1,1] neg_lo:[1,0,0] neg_hi:[1,0,0]
	v_pk_fma_f32 v[98:99], v[154:155], v[90:91], v[138:139] op_sel:[1,0,0]
	v_cvt_pk_bf16_f32 v90, v92, v93
	v_cvt_pk_bf16_f32 v91, v94, v95
	v_cvt_pk_bf16_f32 v92, v88, v89
	v_lshlrev_b64 v[88:89], 11, v[202:203]
	v_lshl_add_u64 v[88:89], s[6:7], 0, v[88:89]
	v_pk_fma_f32 v[80:81], v[174:175], v[128:129], v[80:81] op_sel_hi:[0,1,1] neg_lo:[1,0,0] neg_hi:[1,0,0]
	v_lshl_add_u64 v[88:89], v[88:89], 0, v[190:191]
	v_pk_fma_f32 v[86:87], v[174:175], v[134:135], v[86:87] op_sel_hi:[0,1,1] neg_lo:[1,0,0] neg_hi:[1,0,0]
	v_pk_fma_f32 v[84:85], v[174:175], v[84:85], v[140:141] op_sel:[1,0,0]
	v_pk_fma_f32 v[82:83], v[174:175], v[130:131], v[82:83] op_sel_hi:[0,1,1] neg_lo:[1,0,0] neg_hi:[1,0,0]
	v_pk_fma_f32 v[80:81], v[174:175], v[80:81], v[136:137] op_sel:[1,0,0]
	v_cvt_pk_bf16_f32 v93, v98, v99
	global_store_dwordx4 v[88:89], v[90:93], off
	v_pk_fma_f32 v[86:87], v[174:175], v[86:87], v[142:143] op_sel:[1,0,0]
	v_pk_fma_f32 v[76:77], v[176:177], v[132:133], v[76:77] op_sel_hi:[0,1,1] neg_lo:[1,0,0] neg_hi:[1,0,0]
	v_pk_fma_f32 v[90:91], v[174:175], v[82:83], v[138:139] op_sel:[1,0,0]
	v_cvt_pk_bf16_f32 v82, v84, v85
	v_cvt_pk_bf16_f32 v83, v86, v87
	v_cvt_pk_bf16_f32 v84, v80, v81
	v_lshlrev_b64 v[80:81], 11, v[194:195]
	v_lshl_add_u64 v[80:81], s[6:7], 0, v[80:81]
	v_pk_fma_f32 v[72:73], v[176:177], v[128:129], v[72:73] op_sel_hi:[0,1,1] neg_lo:[1,0,0] neg_hi:[1,0,0]
	v_lshl_add_u64 v[80:81], v[80:81], 0, v[190:191]
	v_pk_fma_f32 v[78:79], v[176:177], v[134:135], v[78:79] op_sel_hi:[0,1,1] neg_lo:[1,0,0] neg_hi:[1,0,0]
	v_pk_fma_f32 v[76:77], v[176:177], v[76:77], v[140:141] op_sel:[1,0,0]
	v_pk_fma_f32 v[74:75], v[176:177], v[130:131], v[74:75] op_sel_hi:[0,1,1] neg_lo:[1,0,0] neg_hi:[1,0,0]
	v_pk_fma_f32 v[72:73], v[176:177], v[72:73], v[136:137] op_sel:[1,0,0]
	v_cvt_pk_bf16_f32 v85, v90, v91
	global_store_dwordx4 v[80:81], v[82:85], off
	v_pk_fma_f32 v[78:79], v[176:177], v[78:79], v[142:143] op_sel:[1,0,0]
	v_pk_fma_f32 v[60:61], v[158:159], v[132:133], v[60:61] op_sel_hi:[0,1,1] neg_lo:[1,0,0] neg_hi:[1,0,0]
	v_pk_fma_f32 v[82:83], v[176:177], v[74:75], v[138:139] op_sel:[1,0,0]
	v_cvt_pk_bf16_f32 v74, v76, v77
	v_cvt_pk_bf16_f32 v75, v78, v79
	v_cvt_pk_bf16_f32 v76, v72, v73
	v_lshlrev_b64 v[72:73], 11, v[188:189]
	v_lshl_add_u64 v[72:73], s[6:7], 0, v[72:73]
	v_lshl_add_u64 v[72:73], v[72:73], 0, v[190:191]
	v_pk_fma_f32 v[60:61], v[158:159], v[60:61], v[140:141] op_sel:[1,0,0]
	v_pk_fma_f32 v[56:57], v[158:159], v[128:129], v[56:57] op_sel_hi:[0,1,1] neg_lo:[1,0,0] neg_hi:[1,0,0]
	v_pk_fma_f32 v[58:59], v[158:159], v[130:131], v[58:59] op_sel_hi:[0,1,1] neg_lo:[1,0,0] neg_hi:[1,0,0]
	v_cvt_pk_bf16_f32 v77, v82, v83
	global_store_dwordx4 v[72:73], v[74:77], off
	v_pk_fma_f32 v[62:63], v[158:159], v[134:135], v[62:63] op_sel_hi:[0,1,1] neg_lo:[1,0,0] neg_hi:[1,0,0]
	v_pk_fma_f32 v[62:63], v[158:159], v[62:63], v[142:143] op_sel:[1,0,0]
	v_pk_fma_f32 v[74:75], v[158:159], v[58:59], v[138:139] op_sel:[1,0,0]
	v_pk_fma_f32 v[58:59], v[158:159], v[56:57], v[136:137] op_sel:[1,0,0]
	v_cvt_pk_bf16_f32 v56, v60, v61
	v_lshlrev_b64 v[60:61], 11, v[184:185]
	v_lshl_add_u64 v[60:61], s[6:7], 0, v[60:61]
	v_lshl_add_u64 v[78:79], v[60:61], 0, v[190:191]
	v_cvt_pk_bf16_f32 v57, v62, v63
	v_cvt_pk_bf16_f32 v58, v58, v59
	v_cvt_pk_bf16_f32 v59, v74, v75
	global_store_dwordx4 v[78:79], v[56:59], off
	s_nop 1
	v_mov_b64_e32 v[56:57], v[210:211]
	v_mov_b64_e32 v[58:59], v[212:213]
	v_mov_b64_e32 v[60:61], v[214:215]
	v_mov_b64_e32 v[62:63], v[216:217]
	v_mov_b64_e32 v[74:75], v[218:219]
	v_mov_b64_e32 v[76:77], v[220:221]
	v_mov_b64_e32 v[82:83], v[222:223]
	v_mov_b64_e32 v[84:85], v[234:235]
	s_mov_b64 s[6:7], -1
	v_pk_fma_f32 v[68:69], v[160:161], v[56:57], v[68:69] op_sel_hi:[0,1,1] neg_lo:[1,0,0] neg_hi:[1,0,0]
	v_pk_fma_f32 v[70:71], v[160:161], v[58:59], v[70:71] op_sel_hi:[0,1,1] neg_lo:[1,0,0] neg_hi:[1,0,0]
; __device__ __forceinline__ u32x4 pack8(const f32x4 v0, const f32x4 v1) { u32x4 w; w.x = cvt_pk_bf16(v0[0], v0[1]); w.y = cvt_pk_bf16(v0[2], v0[3]); w.z = cvt_pk_bf16(v1[0], v1[1]); w.w = cvt_pk_bf16(v1[2], v1[3]); return w; }
;     __device__ __forceinline__ void operator()(const f32x4 (&acc)[2][2][4][2], const Unit& u, int wr, int wc, int fr, int fq) const {
;     ...
;         for (int bj = 0; bj < 2; ++bj) { const f32x4 s0 = *(const f32x4*)(cs + col0 + bj * HALF), s1 = *(const f32x4*)(cs + col0 + bj * HALF + 4), b0 = *(const f32x4*)(cb + col0 + bj * HALF), b1 = *(const f32x4*)(cb + col0 + bj * HALF + 4);
; #pragma unroll
;             for (int ai = 0; ai < 2; ++ai)
; #pragma unroll
;                 for (int m = 0; m < 4; ++m) { const f32x4 v0 = (acc[ai][bj][m][0] - s0 * mu[ai][m]) * rs[ai][m] + b0, v1 = (acc[ai][bj][m][1] - s1 * mu[ai][m]) * rs[ai][m] + b1;
;                     *(u32x4*)(O + (size_t)(row0 + ai * HALF + m * 16) * ldc + col0 + bj * HALF) = pack8(v0, v1); } }
	v_pk_fma_f32 v[64:65], v[160:161], v[74:75], v[64:65] op_sel_hi:[0,1,1] neg_lo:[1,0,0] neg_hi:[1,0,0]
	v_pk_fma_f32 v[66:67], v[160:161], v[76:77], v[66:67] op_sel_hi:[0,1,1] neg_lo:[1,0,0] neg_hi:[1,0,0]
	v_pk_fma_f32 v[70:71], v[160:161], v[70:71], v[62:63] op_sel:[1,0,0]
	v_pk_fma_f32 v[68:69], v[160:161], v[68:69], v[60:61] op_sel:[1,0,0]
	v_pk_fma_f32 v[86:87], v[160:161], v[66:67], v[84:85] op_sel:[1,0,0]
	v_pk_fma_f32 v[66:67], v[160:161], v[64:65], v[82:83] op_sel:[1,0,0]
	v_cvt_pk_bf16_f32 v64, v68, v69
	v_cvt_pk_bf16_f32 v65, v70, v71
	v_pk_fma_f32 v[52:53], v[178:179], v[56:57], v[52:53] op_sel_hi:[0,1,1] neg_lo:[1,0,0] neg_hi:[1,0,0]
	v_pk_fma_f32 v[54:55], v[178:179], v[58:59], v[54:55] op_sel_hi:[0,1,1] neg_lo:[1,0,0] neg_hi:[1,0,0]
	v_pk_fma_f32 v[48:49], v[178:179], v[74:75], v[48:49] op_sel_hi:[0,1,1] neg_lo:[1,0,0] neg_hi:[1,0,0]
	v_pk_fma_f32 v[50:51], v[178:179], v[76:77], v[50:51] op_sel_hi:[0,1,1] neg_lo:[1,0,0] neg_hi:[1,0,0]
	v_cvt_pk_bf16_f32 v66, v66, v67
	v_cvt_pk_bf16_f32 v67, v86, v87
	global_store_dwordx4 v[204:205], v[64:67], off offset:256
	v_pk_fma_f32 v[54:55], v[178:179], v[54:55], v[62:63] op_sel:[1,0,0]
	v_pk_fma_f32 v[52:53], v[178:179], v[52:53], v[60:61] op_sel:[1,0,0]
	v_pk_fma_f32 v[64:65], v[178:179], v[50:51], v[84:85] op_sel:[1,0,0]
	v_pk_fma_f32 v[50:51], v[178:179], v[48:49], v[82:83] op_sel:[1,0,0]
	v_cvt_pk_bf16_f32 v48, v52, v53
	v_cvt_pk_bf16_f32 v49, v54, v55
	v_pk_fma_f32 v[44:45], v[162:163], v[56:57], v[44:45] op_sel_hi:[0,1,1] neg_lo:[1,0,0] neg_hi:[1,0,0]
	v_pk_fma_f32 v[46:47], v[162:163], v[58:59], v[46:47] op_sel_hi:[0,1,1] neg_lo:[1,0,0] neg_hi:[1,0,0]
	v_pk_fma_f32 v[40:41], v[162:163], v[74:75], v[40:41] op_sel_hi:[0,1,1] neg_lo:[1,0,0] neg_hi:[1,0,0]
	v_pk_fma_f32 v[42:43], v[162:163], v[76:77], v[42:43] op_sel_hi:[0,1,1] neg_lo:[1,0,0] neg_hi:[1,0,0]
	v_cvt_pk_bf16_f32 v50, v50, v51
	v_cvt_pk_bf16_f32 v51, v64, v65
	global_store_dwordx4 v[192:193], v[48:51], off offset:256
	v_pk_fma_f32 v[46:47], v[162:163], v[46:47], v[62:63] op_sel:[1,0,0]
	v_pk_fma_f32 v[44:45], v[162:163], v[44:45], v[60:61] op_sel:[1,0,0]
	v_pk_fma_f32 v[48:49], v[162:163], v[42:43], v[84:85] op_sel:[1,0,0]
	v_pk_fma_f32 v[42:43], v[162:163], v[40:41], v[82:83] op_sel:[1,0,0]
	v_cvt_pk_bf16_f32 v40, v44, v45
	v_cvt_pk_bf16_f32 v41, v46, v47
	v_pk_fma_f32 v[36:37], v[156:157], v[56:57], v[36:37] op_sel_hi:[0,1,1] neg_lo:[1,0,0] neg_hi:[1,0,0]
	v_pk_fma_f32 v[38:39], v[156:157], v[58:59], v[38:39] op_sel_hi:[0,1,1] neg_lo:[1,0,0] neg_hi:[1,0,0]
	v_pk_fma_f32 v[32:33], v[156:157], v[74:75], v[32:33] op_sel_hi:[0,1,1] neg_lo:[1,0,0] neg_hi:[1,0,0]
	v_pk_fma_f32 v[34:35], v[156:157], v[76:77], v[34:35] op_sel_hi:[0,1,1] neg_lo:[1,0,0] neg_hi:[1,0,0]
	v_cvt_pk_bf16_f32 v42, v42, v43
	v_cvt_pk_bf16_f32 v43, v48, v49
	global_store_dwordx4 v[186:187], v[40:43], off offset:256
	v_pk_fma_f32 v[38:39], v[156:157], v[38:39], v[62:63] op_sel:[1,0,0]
	v_pk_fma_f32 v[36:37], v[156:157], v[36:37], v[60:61] op_sel:[1,0,0]
	v_pk_fma_f32 v[40:41], v[156:157], v[34:35], v[84:85] op_sel:[1,0,0]
	v_pk_fma_f32 v[34:35], v[156:157], v[32:33], v[82:83] op_sel:[1,0,0]
	v_cvt_pk_bf16_f32 v32, v36, v37
	v_cvt_pk_bf16_f32 v33, v38, v39
	v_pk_fma_f32 v[28:29], v[154:155], v[56:57], v[28:29] op_sel_hi:[0,1,1] neg_lo:[1,0,0] neg_hi:[1,0,0]
	v_pk_fma_f32 v[30:31], v[154:155], v[58:59], v[30:31] op_sel_hi:[0,1,1] neg_lo:[1,0,0] neg_hi:[1,0,0]
	v_pk_fma_f32 v[24:25], v[154:155], v[74:75], v[24:25] op_sel_hi:[0,1,1] neg_lo:[1,0,0] neg_hi:[1,0,0]
	v_pk_fma_f32 v[26:27], v[154:155], v[76:77], v[26:27] op_sel_hi:[0,1,1] neg_lo:[1,0,0] neg_hi:[1,0,0]
	v_cvt_pk_bf16_f32 v34, v34, v35
	v_cvt_pk_bf16_f32 v35, v40, v41
	global_store_dwordx4 v[96:97], v[32:35], off offset:256
	v_pk_fma_f32 v[30:31], v[154:155], v[30:31], v[62:63] op_sel:[1,0,0]
	v_pk_fma_f32 v[28:29], v[154:155], v[28:29], v[60:61] op_sel:[1,0,0]
	v_pk_fma_f32 v[32:33], v[154:155], v[26:27], v[84:85] op_sel:[1,0,0]
	v_pk_fma_f32 v[26:27], v[154:155], v[24:25], v[82:83] op_sel:[1,0,0]
	v_cvt_pk_bf16_f32 v24, v28, v29
	v_cvt_pk_bf16_f32 v25, v30, v31
	v_pk_fma_f32 v[20:21], v[174:175], v[56:57], v[20:21] op_sel_hi:[0,1,1] neg_lo:[1,0,0] neg_hi:[1,0,0]
	v_pk_fma_f32 v[22:23], v[174:175], v[58:59], v[22:23] op_sel_hi:[0,1,1] neg_lo:[1,0,0] neg_hi:[1,0,0]
	v_pk_fma_f32 v[16:17], v[174:175], v[74:75], v[16:17] op_sel_hi:[0,1,1] neg_lo:[1,0,0] neg_hi:[1,0,0]
	v_pk_fma_f32 v[18:19], v[174:175], v[76:77], v[18:19] op_sel_hi:[0,1,1] neg_lo:[1,0,0] neg_hi:[1,0,0]
	v_cvt_pk_bf16_f32 v26, v26, v27
	v_cvt_pk_bf16_f32 v27, v32, v33
	global_store_dwordx4 v[88:89], v[24:27], off offset:256
	v_pk_fma_f32 v[22:23], v[174:175], v[22:23], v[62:63] op_sel:[1,0,0]
	v_pk_fma_f32 v[20:21], v[174:175], v[20:21], v[60:61] op_sel:[1,0,0]
	v_pk_fma_f32 v[24:25], v[174:175], v[18:19], v[84:85] op_sel:[1,0,0]
	v_pk_fma_f32 v[18:19], v[174:175], v[16:17], v[82:83] op_sel:[1,0,0]
	v_cvt_pk_bf16_f32 v16, v20, v21
	v_cvt_pk_bf16_f32 v17, v22, v23
	v_pk_fma_f32 v[12:13], v[176:177], v[56:57], v[12:13] op_sel_hi:[0,1,1] neg_lo:[1,0,0] neg_hi:[1,0,0]
	v_pk_fma_f32 v[14:15], v[176:177], v[58:59], v[14:15] op_sel_hi:[0,1,1] neg_lo:[1,0,0] neg_hi:[1,0,0]
	v_pk_fma_f32 v[8:9], v[176:177], v[74:75], v[8:9] op_sel_hi:[0,1,1] neg_lo:[1,0,0] neg_hi:[1,0,0]
	v_pk_fma_f32 v[10:11], v[176:177], v[76:77], v[10:11] op_sel_hi:[0,1,1] neg_lo:[1,0,0] neg_hi:[1,0,0]
	v_cvt_pk_bf16_f32 v18, v18, v19
	v_cvt_pk_bf16_f32 v19, v24, v25
	global_store_dwordx4 v[80:81], v[16:19], off offset:256
	v_pk_fma_f32 v[14:15], v[176:177], v[14:15], v[62:63] op_sel:[1,0,0]
	v_pk_fma_f32 v[12:13], v[176:177], v[12:13], v[60:61] op_sel:[1,0,0]
	v_pk_fma_f32 v[16:17], v[176:177], v[10:11], v[84:85] op_sel:[1,0,0]
	v_pk_fma_f32 v[10:11], v[176:177], v[8:9], v[82:83] op_sel:[1,0,0]
	v_cvt_pk_bf16_f32 v8, v12, v13
	v_cvt_pk_bf16_f32 v9, v14, v15
	v_pk_fma_f32 v[0:1], v[158:159], v[74:75], v[0:1] op_sel_hi:[0,1,1] neg_lo:[1,0,0] neg_hi:[1,0,0]
	v_pk_fma_f32 v[2:3], v[158:159], v[76:77], v[2:3] op_sel_hi:[0,1,1] neg_lo:[1,0,0] neg_hi:[1,0,0]
	v_cvt_pk_bf16_f32 v10, v10, v11
	v_cvt_pk_bf16_f32 v11, v16, v17
	global_store_dwordx4 v[72:73], v[8:11], off offset:256
	v_pk_fma_f32 v[4:5], v[158:159], v[56:57], v[4:5] op_sel_hi:[0,1,1] neg_lo:[1,0,0] neg_hi:[1,0,0]
	v_pk_fma_f32 v[6:7], v[158:159], v[58:59], v[6:7] op_sel_hi:[0,1,1] neg_lo:[1,0,0] neg_hi:[1,0,0]
	v_pk_fma_f32 v[8:9], v[158:159], v[2:3], v[84:85] op_sel:[1,0,0]
	v_pk_fma_f32 v[2:3], v[158:159], v[0:1], v[82:83] op_sel:[1,0,0]
	v_pk_fma_f32 v[6:7], v[158:159], v[6:7], v[62:63] op_sel:[1,0,0]
	v_pk_fma_f32 v[4:5], v[158:159], v[4:5], v[60:61] op_sel:[1,0,0]
	s_nop 0
	v_cvt_pk_bf16_f32 v0, v4, v5
	v_cvt_pk_bf16_f32 v1, v6, v7
	v_cvt_pk_bf16_f32 v2, v2, v3
	v_cvt_pk_bf16_f32 v3, v8, v9
	global_store_dwordx4 v[78:79], v[0:3], off offset:256
	s_cbranch_vccnz .LBB0_108
	s_andn2_b64 vcc, exec, s[4:5]
	s_cbranch_vccnz .LBB0_107
	s_barrier
	s_branch .LBB0_107

; __device__ __forceinline__ u32x4 pack8(const f32x4 v0, const f32x4 v1) { u32x4 w; w.x = cvt_pk_bf16(v0[0], v0[1]); w.y = cvt_pk_bf16(v0[2], v0[3]); w.z = cvt_pk_bf16(v1[0], v1[1]); w.w = cvt_pk_bf16(v1[2], v1[3]); return w; }
;     __device__ __forceinline__ void operator()(const f32x4 (&acc)[2][2][4][2], const Unit& u, int wr, int wc, int fr, int fq) const {
;     ...
;         if (u.pn >= 4) {
; #pragma unroll
;             for (int bj = 0; bj < 2; ++bj) { const f32x4 s0 = *(const f32x4*)(cs + col0 + bj * HALF), s1 = *(const f32x4*)(cs + col0 + bj * HALF + 4), b0 = *(const f32x4*)(cb + col0 + bj * HALF), b1 = *(const f32x4*)(cb + col0 + bj * HALF + 4);
; #pragma unroll
;                 for (int ai = 0; ai < 2; ++ai)
; #pragma unroll
;                     for (int m = 0; m < 4; ++m) { const f32x4 v0 = (acc[ai][bj][m][0] - s0 * mu[ai][m]) * rs[ai][m] + b0, v1 = (acc[ai][bj][m][1] - s1 * mu[ai][m]) * rs[ai][m] + b1;
;                         *(u32x4*)(O + (size_t)(row0 + ai * HALF + m * 16) * ldc + col0 + bj * HALF) = pack8(v0, v1); } }
.LBB0_737:
	v_readlane_b32 s4, v254, 16
	v_lshlrev_b64 v[136:137], 2, v[164:165]
	v_readlane_b32 s5, v254, 17
	s_movk_i32 s15, 0x1400
	s_nop 0
	v_lshl_add_u64 v[144:145], s[4:5], 0, v[136:137]
	v_readlane_b32 s4, v253, 51
	v_readlane_b32 s5, v253, 52
	global_load_dwordx4 v[128:131], v[144:145], off offset:16
	global_load_dwordx4 v[132:135], v[144:145], off
	v_lshl_add_u64 v[146:147], s[4:5], 0, v[136:137]
	global_load_dwordx4 v[136:139], v[146:147], off offset:16
	global_load_dwordx4 v[140:143], v[146:147], off
	global_load_dwordx4 v[152:155], v[144:145], off offset:528
	global_load_dwordx4 v[156:159], v[144:145], off offset:512
	global_load_dwordx4 v[160:163], v[146:147], off offset:528
	global_load_dwordx2 v[218:219], v[146:147], off offset:512
	global_load_dwordx2 v[236:237], v[146:147], off offset:520
	v_readlane_b32 s4, v252, 36
	v_readlane_b32 s5, v252, 37
	s_waitcnt vmcnt(0)
	v_pk_fma_f32 v[122:123], v[200:201], v[130:131], v[122:123] op_sel_hi:[0,1,1] neg_lo:[1,0,0] neg_hi:[1,0,0]
	v_pk_fma_f32 v[126:127], v[200:201], v[134:135], v[126:127] op_sel_hi:[0,1,1] neg_lo:[1,0,0] neg_hi:[1,0,0]
	v_pk_fma_f32 v[124:125], v[200:201], v[132:133], v[124:125] op_sel_hi:[0,1,1] neg_lo:[1,0,0] neg_hi:[1,0,0]
	v_pk_fma_f32 v[120:121], v[200:201], v[128:129], v[120:121] op_sel_hi:[0,1,1] neg_lo:[1,0,0] neg_hi:[1,0,0]
	v_pk_fma_f32 v[122:123], v[200:201], v[122:123], v[138:139] op_sel:[1,0,0]
	v_pk_fma_f32 v[126:127], v[200:201], v[126:127], v[142:143] op_sel:[1,0,0]
	v_pk_fma_f32 v[124:125], v[200:201], v[124:125], v[140:141] op_sel:[1,0,0]
	v_pk_fma_f32 v[120:121], v[200:201], v[120:121], v[136:137] op_sel:[1,0,0]
	v_cvt_pk_bf16_f32 v148, v124, v125
	v_cvt_pk_bf16_f32 v149, v126, v127
	v_lshlrev_b64 v[124:125], 1, v[164:165]
	v_cvt_pk_bf16_f32 v150, v120, v121
	v_cvt_pk_bf16_f32 v151, v122, v123
	v_mov_b64_e32 v[122:123], s[4:5]
	v_mad_i64_i32 v[120:121], s[4:5], v216, s15, v[122:123]
	v_pk_fma_f32 v[116:117], v[198:199], v[132:133], v[116:117] op_sel_hi:[0,1,1] neg_lo:[1,0,0] neg_hi:[1,0,0]
	v_pk_fma_f32 v[112:113], v[198:199], v[128:129], v[112:113] op_sel_hi:[0,1,1] neg_lo:[1,0,0] neg_hi:[1,0,0]
	v_lshl_add_u64 v[120:121], v[120:121], 0, v[124:125]
	v_pk_fma_f32 v[118:119], v[198:199], v[134:135], v[118:119] op_sel_hi:[0,1,1] neg_lo:[1,0,0] neg_hi:[1,0,0]
	v_pk_fma_f32 v[116:117], v[198:199], v[116:117], v[140:141] op_sel:[1,0,0]
	v_pk_fma_f32 v[114:115], v[198:199], v[130:131], v[114:115] op_sel_hi:[0,1,1] neg_lo:[1,0,0] neg_hi:[1,0,0]
	v_pk_fma_f32 v[112:113], v[198:199], v[112:113], v[136:137] op_sel:[1,0,0]
	global_store_dwordx4 v[120:121], v[148:151], off
	v_pk_fma_f32 v[118:119], v[198:199], v[118:119], v[142:143] op_sel:[1,0,0]
	v_pk_fma_f32 v[126:127], v[198:199], v[114:115], v[138:139] op_sel:[1,0,0]
	v_cvt_pk_bf16_f32 v114, v116, v117
	v_cvt_pk_bf16_f32 v115, v118, v119
	v_cvt_pk_bf16_f32 v116, v112, v113
	v_mad_i64_i32 v[112:113], s[4:5], v214, s15, v[122:123]
	v_pk_fma_f32 v[108:109], v[196:197], v[132:133], v[108:109] op_sel_hi:[0,1,1] neg_lo:[1,0,0] neg_hi:[1,0,0]
	v_pk_fma_f32 v[104:105], v[196:197], v[128:129], v[104:105] op_sel_hi:[0,1,1] neg_lo:[1,0,0] neg_hi:[1,0,0]
	v_lshl_add_u64 v[112:113], v[112:113], 0, v[124:125]
	v_pk_fma_f32 v[110:111], v[196:197], v[134:135], v[110:111] op_sel_hi:[0,1,1] neg_lo:[1,0,0] neg_hi:[1,0,0]
	v_pk_fma_f32 v[108:109], v[196:197], v[108:109], v[140:141] op_sel:[1,0,0]
	v_pk_fma_f32 v[106:107], v[196:197], v[130:131], v[106:107] op_sel_hi:[0,1,1] neg_lo:[1,0,0] neg_hi:[1,0,0]
	v_pk_fma_f32 v[104:105], v[196:197], v[104:105], v[136:137] op_sel:[1,0,0]
	v_cvt_pk_bf16_f32 v117, v126, v127
	global_store_dwordx4 v[112:113], v[114:117], off
	v_pk_fma_f32 v[110:111], v[196:197], v[110:111], v[142:143] op_sel:[1,0,0]
	v_pk_fma_f32 v[100:101], v[194:195], v[132:133], v[100:101] op_sel_hi:[0,1,1] neg_lo:[1,0,0] neg_hi:[1,0,0]
	v_pk_fma_f32 v[114:115], v[196:197], v[106:107], v[138:139] op_sel:[1,0,0]
	v_cvt_pk_bf16_f32 v106, v108, v109
	v_cvt_pk_bf16_f32 v107, v110, v111
	v_cvt_pk_bf16_f32 v108, v104, v105
	v_mad_i64_i32 v[104:105], s[4:5], v212, s15, v[122:123]
	v_pk_fma_f32 v[96:97], v[194:195], v[128:129], v[96:97] op_sel_hi:[0,1,1] neg_lo:[1,0,0] neg_hi:[1,0,0]
	v_lshl_add_u64 v[104:105], v[104:105], 0, v[124:125]
	v_pk_fma_f32 v[102:103], v[194:195], v[134:135], v[102:103] op_sel_hi:[0,1,1] neg_lo:[1,0,0] neg_hi:[1,0,0]
	v_pk_fma_f32 v[100:101], v[194:195], v[100:101], v[140:141] op_sel:[1,0,0]
	v_pk_fma_f32 v[98:99], v[194:195], v[130:131], v[98:99] op_sel_hi:[0,1,1] neg_lo:[1,0,0] neg_hi:[1,0,0]
	v_pk_fma_f32 v[96:97], v[194:195], v[96:97], v[136:137] op_sel:[1,0,0]
	v_cvt_pk_bf16_f32 v109, v114, v115
	global_store_dwordx4 v[104:105], v[106:109], off
	v_pk_fma_f32 v[102:103], v[194:195], v[102:103], v[142:143] op_sel:[1,0,0]
	v_pk_fma_f32 v[92:93], v[192:193], v[132:133], v[92:93] op_sel_hi:[0,1,1] neg_lo:[1,0,0] neg_hi:[1,0,0]
	v_pk_fma_f32 v[106:107], v[194:195], v[98:99], v[138:139] op_sel:[1,0,0]
	v_cvt_pk_bf16_f32 v98, v100, v101
	v_cvt_pk_bf16_f32 v99, v102, v103
	v_cvt_pk_bf16_f32 v100, v96, v97
	v_mad_i64_i32 v[96:97], s[4:5], v210, s15, v[122:123]
	v_pk_fma_f32 v[88:89], v[192:193], v[128:129], v[88:89] op_sel_hi:[0,1,1] neg_lo:[1,0,0] neg_hi:[1,0,0]
	v_lshl_add_u64 v[96:97], v[96:97], 0, v[124:125]
	v_pk_fma_f32 v[94:95], v[192:193], v[134:135], v[94:95] op_sel_hi:[0,1,1] neg_lo:[1,0,0] neg_hi:[1,0,0]
	v_pk_fma_f32 v[92:93], v[192:193], v[92:93], v[140:141] op_sel:[1,0,0]
	v_pk_fma_f32 v[90:91], v[192:193], v[130:131], v[90:91] op_sel_hi:[0,1,1] neg_lo:[1,0,0] neg_hi:[1,0,0]
	v_pk_fma_f32 v[88:89], v[192:193], v[88:89], v[136:137] op_sel:[1,0,0]
	v_cvt_pk_bf16_f32 v101, v106, v107
; __device__ __forceinline__ u32x4 pack8(const f32x4 v0, const f32x4 v1) { u32x4 w; w.x = cvt_pk_bf16(v0[0], v0[1]); w.y = cvt_pk_bf16(v0[2], v0[3]); w.z = cvt_pk_bf16(v1[0], v1[1]); w.w = cvt_pk_bf16(v1[2], v1[3]); return w; }
;     __device__ __forceinline__ void operator()(const f32x4 (&acc)[2][2][4][2], const Unit& u, int wr, int wc, int fr, int fq) const {
;     ...
;         if (u.pn >= 4) {
; #pragma unroll
;             for (int bj = 0; bj < 2; ++bj) { const f32x4 s0 = *(const f32x4*)(cs + col0 + bj * HALF), s1 = *(const f32x4*)(cs + col0 + bj * HALF + 4), b0 = *(const f32x4*)(cb + col0 + bj * HALF), b1 = *(const f32x4*)(cb + col0 + bj * HALF + 4);
; #pragma unroll
;                 for (int ai = 0; ai < 2; ++ai)
; #pragma unroll
;                     for (int m = 0; m < 4; ++m) { const f32x4 v0 = (acc[ai][bj][m][0] - s0 * mu[ai][m]) * rs[ai][m] + b0, v1 = (acc[ai][bj][m][1] - s1 * mu[ai][m]) * rs[ai][m] + b1;
;                         *(u32x4*)(O + (size_t)(row0 + ai * HALF + m * 16) * ldc + col0 + bj * HALF) = pack8(v0, v1); } }
	global_store_dwordx4 v[96:97], v[98:101], off
	v_pk_fma_f32 v[94:95], v[192:193], v[94:95], v[142:143] op_sel:[1,0,0]
	v_pk_fma_f32 v[84:85], v[190:191], v[132:133], v[84:85] op_sel_hi:[0,1,1] neg_lo:[1,0,0] neg_hi:[1,0,0]
	v_pk_fma_f32 v[98:99], v[192:193], v[90:91], v[138:139] op_sel:[1,0,0]
	v_cvt_pk_bf16_f32 v90, v92, v93
	v_cvt_pk_bf16_f32 v91, v94, v95
	v_cvt_pk_bf16_f32 v92, v88, v89
	v_mad_i64_i32 v[88:89], s[4:5], v208, s15, v[122:123]
	v_pk_fma_f32 v[80:81], v[190:191], v[128:129], v[80:81] op_sel_hi:[0,1,1] neg_lo:[1,0,0] neg_hi:[1,0,0]
	v_lshl_add_u64 v[88:89], v[88:89], 0, v[124:125]
	v_pk_fma_f32 v[86:87], v[190:191], v[134:135], v[86:87] op_sel_hi:[0,1,1] neg_lo:[1,0,0] neg_hi:[1,0,0]
	v_pk_fma_f32 v[84:85], v[190:191], v[84:85], v[140:141] op_sel:[1,0,0]
	v_pk_fma_f32 v[82:83], v[190:191], v[130:131], v[82:83] op_sel_hi:[0,1,1] neg_lo:[1,0,0] neg_hi:[1,0,0]
	v_pk_fma_f32 v[80:81], v[190:191], v[80:81], v[136:137] op_sel:[1,0,0]
	v_cvt_pk_bf16_f32 v93, v98, v99
	global_store_dwordx4 v[88:89], v[90:93], off
	v_pk_fma_f32 v[86:87], v[190:191], v[86:87], v[142:143] op_sel:[1,0,0]
	v_pk_fma_f32 v[76:77], v[188:189], v[132:133], v[76:77] op_sel_hi:[0,1,1] neg_lo:[1,0,0] neg_hi:[1,0,0]
	v_pk_fma_f32 v[90:91], v[190:191], v[82:83], v[138:139] op_sel:[1,0,0]
	v_cvt_pk_bf16_f32 v82, v84, v85
	v_cvt_pk_bf16_f32 v83, v86, v87
	v_cvt_pk_bf16_f32 v84, v80, v81
	v_mad_i64_i32 v[80:81], s[4:5], v206, s15, v[122:123]
	v_lshl_add_u64 v[80:81], v[80:81], 0, v[124:125]
	v_pk_fma_f32 v[76:77], v[188:189], v[76:77], v[140:141] op_sel:[1,0,0]
	v_pk_fma_f32 v[74:75], v[188:189], v[130:131], v[74:75] op_sel_hi:[0,1,1] neg_lo:[1,0,0] neg_hi:[1,0,0]
	v_pk_fma_f32 v[72:73], v[188:189], v[128:129], v[72:73] op_sel_hi:[0,1,1] neg_lo:[1,0,0] neg_hi:[1,0,0]
	v_cvt_pk_bf16_f32 v85, v90, v91
	global_store_dwordx4 v[80:81], v[82:85], off
	v_pk_fma_f32 v[78:79], v[188:189], v[134:135], v[78:79] op_sel_hi:[0,1,1] neg_lo:[1,0,0] neg_hi:[1,0,0]
	v_pk_fma_f32 v[64:65], v[186:187], v[132:133], v[64:65] op_sel_hi:[0,1,1] neg_lo:[1,0,0] neg_hi:[1,0,0]
	v_pk_fma_f32 v[82:83], v[188:189], v[74:75], v[138:139] op_sel:[1,0,0]
	v_pk_fma_f32 v[74:75], v[188:189], v[72:73], v[136:137] op_sel:[1,0,0]
	v_cvt_pk_bf16_f32 v72, v76, v77
	v_mad_i64_i32 v[76:77], s[4:5], v204, s15, v[122:123]
	v_pk_fma_f32 v[78:79], v[188:189], v[78:79], v[142:143] op_sel:[1,0,0]
	v_pk_fma_f32 v[64:65], v[186:187], v[64:65], v[140:141] op_sel:[1,0,0]
	v_cvt_pk_bf16_f32 v73, v78, v79
	v_cvt_pk_bf16_f32 v74, v74, v75
	v_cvt_pk_bf16_f32 v75, v82, v83
	v_lshl_add_u64 v[82:83], v[76:77], 0, v[124:125]
	v_pk_fma_f32 v[62:63], v[186:187], v[130:131], v[62:63] op_sel_hi:[0,1,1] neg_lo:[1,0,0] neg_hi:[1,0,0]
	v_pk_fma_f32 v[60:61], v[186:187], v[128:129], v[60:61] op_sel_hi:[0,1,1] neg_lo:[1,0,0] neg_hi:[1,0,0]
	global_store_dwordx4 v[82:83], v[72:75], off
	v_pk_fma_f32 v[66:67], v[186:187], v[134:135], v[66:67] op_sel_hi:[0,1,1] neg_lo:[1,0,0] neg_hi:[1,0,0]
	v_pk_fma_f32 v[66:67], v[186:187], v[66:67], v[142:143] op_sel:[1,0,0]
	v_pk_fma_f32 v[72:73], v[186:187], v[62:63], v[138:139] op_sel:[1,0,0]
	v_pk_fma_f32 v[62:63], v[186:187], v[60:61], v[136:137] op_sel:[1,0,0]
	v_cvt_pk_bf16_f32 v60, v64, v65
	v_mad_i64_i32 v[64:65], s[4:5], v202, s15, v[122:123]
	v_lshl_add_u64 v[84:85], v[64:65], 0, v[124:125]
	v_cvt_pk_bf16_f32 v61, v66, v67
	v_cvt_pk_bf16_f32 v62, v62, v63
	v_cvt_pk_bf16_f32 v63, v72, v73
	global_store_dwordx4 v[84:85], v[60:63], off
	s_nop 1
	v_mov_b64_e32 v[60:61], v[152:153]
	v_mov_b64_e32 v[62:63], v[154:155]
	v_mov_b64_e32 v[72:73], v[156:157]
	v_mov_b64_e32 v[74:75], v[158:159]
	v_mov_b64_e32 v[64:65], v[160:161]
	v_mov_b64_e32 v[66:67], v[162:163]
	v_mov_b64_e32 v[76:77], v[218:219]
	v_mov_b64_e32 v[78:79], v[236:237]
	v_pk_fma_f32 v[58:59], v[200:201], v[62:63], v[58:59] op_sel_hi:[0,1,1] neg_lo:[1,0,0] neg_hi:[1,0,0]
	v_pk_fma_f32 v[70:71], v[200:201], v[74:75], v[70:71] op_sel_hi:[0,1,1] neg_lo:[1,0,0] neg_hi:[1,0,0]
	v_pk_fma_f32 v[68:69], v[200:201], v[72:73], v[68:69] op_sel_hi:[0,1,1] neg_lo:[1,0,0] neg_hi:[1,0,0]
	v_pk_fma_f32 v[56:57], v[200:201], v[60:61], v[56:57] op_sel_hi:[0,1,1] neg_lo:[1,0,0] neg_hi:[1,0,0]
	v_pk_fma_f32 v[70:71], v[200:201], v[70:71], v[78:79] op_sel:[1,0,0]
	v_pk_fma_f32 v[68:69], v[200:201], v[68:69], v[76:77] op_sel:[1,0,0]
	v_pk_fma_f32 v[86:87], v[200:201], v[58:59], v[66:67] op_sel:[1,0,0]
	v_pk_fma_f32 v[58:59], v[200:201], v[56:57], v[64:65] op_sel:[1,0,0]
	v_cvt_pk_bf16_f32 v56, v68, v69
	v_cvt_pk_bf16_f32 v57, v70, v71
	v_pk_fma_f32 v[54:55], v[198:199], v[74:75], v[54:55] op_sel_hi:[0,1,1] neg_lo:[1,0,0] neg_hi:[1,0,0]
	v_pk_fma_f32 v[52:53], v[198:199], v[72:73], v[52:53] op_sel_hi:[0,1,1] neg_lo:[1,0,0] neg_hi:[1,0,0]
	v_pk_fma_f32 v[50:51], v[198:199], v[62:63], v[50:51] op_sel_hi:[0,1,1] neg_lo:[1,0,0] neg_hi:[1,0,0]
	v_pk_fma_f32 v[48:49], v[198:199], v[60:61], v[48:49] op_sel_hi:[0,1,1] neg_lo:[1,0,0] neg_hi:[1,0,0]
	v_cvt_pk_bf16_f32 v58, v58, v59
	v_cvt_pk_bf16_f32 v59, v86, v87
	global_store_dwordx4 v[120:121], v[56:59], off offset:256
	v_pk_fma_f32 v[54:55], v[198:199], v[54:55], v[78:79] op_sel:[1,0,0]
	v_pk_fma_f32 v[52:53], v[198:199], v[52:53], v[76:77] op_sel:[1,0,0]
	v_pk_fma_f32 v[56:57], v[198:199], v[50:51], v[66:67] op_sel:[1,0,0]
	v_pk_fma_f32 v[50:51], v[198:199], v[48:49], v[64:65] op_sel:[1,0,0]
	v_cvt_pk_bf16_f32 v48, v52, v53
	v_cvt_pk_bf16_f32 v49, v54, v55
; __device__ __forceinline__ u32x4 pack8(const f32x4 v0, const f32x4 v1) { u32x4 w; w.x = cvt_pk_bf16(v0[0], v0[1]); w.y = cvt_pk_bf16(v0[2], v0[3]); w.z = cvt_pk_bf16(v1[0], v1[1]); w.w = cvt_pk_bf16(v1[2], v1[3]); return w; }
;     __device__ __forceinline__ void operator()(const f32x4 (&acc)[2][2][4][2], const Unit& u, int wr, int wc, int fr, int fq) const {
;     ...
;         if (u.pn >= 4) {
; #pragma unroll
;             for (int bj = 0; bj < 2; ++bj) { const f32x4 s0 = *(const f32x4*)(cs + col0 + bj * HALF), s1 = *(const f32x4*)(cs + col0 + bj * HALF + 4), b0 = *(const f32x4*)(cb + col0 + bj * HALF), b1 = *(const f32x4*)(cb + col0 + bj * HALF + 4);
; #pragma unroll
;                 for (int ai = 0; ai < 2; ++ai)
; #pragma unroll
;                     for (int m = 0; m < 4; ++m) { const f32x4 v0 = (acc[ai][bj][m][0] - s0 * mu[ai][m]) * rs[ai][m] + b0, v1 = (acc[ai][bj][m][1] - s1 * mu[ai][m]) * rs[ai][m] + b1;
;                         *(u32x4*)(O + (size_t)(row0 + ai * HALF + m * 16) * ldc + col0 + bj * HALF) = pack8(v0, v1); } }
	v_pk_fma_f32 v[46:47], v[196:197], v[74:75], v[46:47] op_sel_hi:[0,1,1] neg_lo:[1,0,0] neg_hi:[1,0,0]
	v_pk_fma_f32 v[44:45], v[196:197], v[72:73], v[44:45] op_sel_hi:[0,1,1] neg_lo:[1,0,0] neg_hi:[1,0,0]
	v_pk_fma_f32 v[42:43], v[196:197], v[62:63], v[42:43] op_sel_hi:[0,1,1] neg_lo:[1,0,0] neg_hi:[1,0,0]
	v_pk_fma_f32 v[40:41], v[196:197], v[60:61], v[40:41] op_sel_hi:[0,1,1] neg_lo:[1,0,0] neg_hi:[1,0,0]
	v_cvt_pk_bf16_f32 v50, v50, v51
	v_cvt_pk_bf16_f32 v51, v56, v57
	global_store_dwordx4 v[112:113], v[48:51], off offset:256
	v_pk_fma_f32 v[46:47], v[196:197], v[46:47], v[78:79] op_sel:[1,0,0]
	v_pk_fma_f32 v[44:45], v[196:197], v[44:45], v[76:77] op_sel:[1,0,0]
	v_pk_fma_f32 v[48:49], v[196:197], v[42:43], v[66:67] op_sel:[1,0,0]
	v_pk_fma_f32 v[42:43], v[196:197], v[40:41], v[64:65] op_sel:[1,0,0]
	v_cvt_pk_bf16_f32 v40, v44, v45
	v_cvt_pk_bf16_f32 v41, v46, v47
	v_pk_fma_f32 v[38:39], v[194:195], v[74:75], v[38:39] op_sel_hi:[0,1,1] neg_lo:[1,0,0] neg_hi:[1,0,0]
	v_pk_fma_f32 v[36:37], v[194:195], v[72:73], v[36:37] op_sel_hi:[0,1,1] neg_lo:[1,0,0] neg_hi:[1,0,0]
	v_pk_fma_f32 v[34:35], v[194:195], v[62:63], v[34:35] op_sel_hi:[0,1,1] neg_lo:[1,0,0] neg_hi:[1,0,0]
	v_pk_fma_f32 v[32:33], v[194:195], v[60:61], v[32:33] op_sel_hi:[0,1,1] neg_lo:[1,0,0] neg_hi:[1,0,0]
	v_cvt_pk_bf16_f32 v42, v42, v43
	v_cvt_pk_bf16_f32 v43, v48, v49
	global_store_dwordx4 v[104:105], v[40:43], off offset:256
	v_pk_fma_f32 v[38:39], v[194:195], v[38:39], v[78:79] op_sel:[1,0,0]
	v_pk_fma_f32 v[36:37], v[194:195], v[36:37], v[76:77] op_sel:[1,0,0]
	v_pk_fma_f32 v[40:41], v[194:195], v[34:35], v[66:67] op_sel:[1,0,0]
	v_pk_fma_f32 v[34:35], v[194:195], v[32:33], v[64:65] op_sel:[1,0,0]
	v_cvt_pk_bf16_f32 v32, v36, v37
	v_cvt_pk_bf16_f32 v33, v38, v39
	v_pk_fma_f32 v[30:31], v[192:193], v[74:75], v[30:31] op_sel_hi:[0,1,1] neg_lo:[1,0,0] neg_hi:[1,0,0]
	v_pk_fma_f32 v[28:29], v[192:193], v[72:73], v[28:29] op_sel_hi:[0,1,1] neg_lo:[1,0,0] neg_hi:[1,0,0]
	v_pk_fma_f32 v[26:27], v[192:193], v[62:63], v[26:27] op_sel_hi:[0,1,1] neg_lo:[1,0,0] neg_hi:[1,0,0]
	v_pk_fma_f32 v[24:25], v[192:193], v[60:61], v[24:25] op_sel_hi:[0,1,1] neg_lo:[1,0,0] neg_hi:[1,0,0]
	v_cvt_pk_bf16_f32 v34, v34, v35
	v_cvt_pk_bf16_f32 v35, v40, v41
	global_store_dwordx4 v[96:97], v[32:35], off offset:256
	v_pk_fma_f32 v[30:31], v[192:193], v[30:31], v[78:79] op_sel:[1,0,0]
	v_pk_fma_f32 v[28:29], v[192:193], v[28:29], v[76:77] op_sel:[1,0,0]
	v_pk_fma_f32 v[32:33], v[192:193], v[26:27], v[66:67] op_sel:[1,0,0]
	v_pk_fma_f32 v[26:27], v[192:193], v[24:25], v[64:65] op_sel:[1,0,0]
	v_cvt_pk_bf16_f32 v24, v28, v29
	v_cvt_pk_bf16_f32 v25, v30, v31
	v_pk_fma_f32 v[22:23], v[190:191], v[74:75], v[22:23] op_sel_hi:[0,1,1] neg_lo:[1,0,0] neg_hi:[1,0,0]
	v_pk_fma_f32 v[20:21], v[190:191], v[72:73], v[20:21] op_sel_hi:[0,1,1] neg_lo:[1,0,0] neg_hi:[1,0,0]
	v_pk_fma_f32 v[18:19], v[190:191], v[62:63], v[18:19] op_sel_hi:[0,1,1] neg_lo:[1,0,0] neg_hi:[1,0,0]
	v_pk_fma_f32 v[16:17], v[190:191], v[60:61], v[16:17] op_sel_hi:[0,1,1] neg_lo:[1,0,0] neg_hi:[1,0,0]
	v_cvt_pk_bf16_f32 v26, v26, v27
	v_cvt_pk_bf16_f32 v27, v32, v33
	global_store_dwordx4 v[88:89], v[24:27], off offset:256
	v_pk_fma_f32 v[22:23], v[190:191], v[22:23], v[78:79] op_sel:[1,0,0]
	v_pk_fma_f32 v[20:21], v[190:191], v[20:21], v[76:77] op_sel:[1,0,0]
	v_pk_fma_f32 v[24:25], v[190:191], v[18:19], v[66:67] op_sel:[1,0,0]
	v_pk_fma_f32 v[18:19], v[190:191], v[16:17], v[64:65] op_sel:[1,0,0]
	v_cvt_pk_bf16_f32 v16, v20, v21
	v_cvt_pk_bf16_f32 v17, v22, v23
	v_pk_fma_f32 v[14:15], v[188:189], v[74:75], v[14:15] op_sel_hi:[0,1,1] neg_lo:[1,0,0] neg_hi:[1,0,0]
	v_pk_fma_f32 v[12:13], v[188:189], v[72:73], v[12:13] op_sel_hi:[0,1,1] neg_lo:[1,0,0] neg_hi:[1,0,0]
	v_pk_fma_f32 v[10:11], v[188:189], v[62:63], v[10:11] op_sel_hi:[0,1,1] neg_lo:[1,0,0] neg_hi:[1,0,0]
	v_pk_fma_f32 v[8:9], v[188:189], v[60:61], v[8:9] op_sel_hi:[0,1,1] neg_lo:[1,0,0] neg_hi:[1,0,0]
	v_cvt_pk_bf16_f32 v18, v18, v19
	v_cvt_pk_bf16_f32 v19, v24, v25
	global_store_dwordx4 v[80:81], v[16:19], off offset:256
	v_pk_fma_f32 v[14:15], v[188:189], v[14:15], v[78:79] op_sel:[1,0,0]
	v_pk_fma_f32 v[12:13], v[188:189], v[12:13], v[76:77] op_sel:[1,0,0]
	v_pk_fma_f32 v[16:17], v[188:189], v[10:11], v[66:67] op_sel:[1,0,0]
	v_pk_fma_f32 v[10:11], v[188:189], v[8:9], v[64:65] op_sel:[1,0,0]
	v_cvt_pk_bf16_f32 v8, v12, v13
	v_cvt_pk_bf16_f32 v9, v14, v15
	v_pk_fma_f32 v[2:3], v[186:187], v[62:63], v[2:3] op_sel_hi:[0,1,1] neg_lo:[1,0,0] neg_hi:[1,0,0]
	v_pk_fma_f32 v[0:1], v[186:187], v[60:61], v[0:1] op_sel_hi:[0,1,1] neg_lo:[1,0,0] neg_hi:[1,0,0]
	v_cvt_pk_bf16_f32 v10, v10, v11
	v_cvt_pk_bf16_f32 v11, v16, v17
	global_store_dwordx4 v[82:83], v[8:11], off offset:256
	v_pk_fma_f32 v[6:7], v[186:187], v[74:75], v[6:7] op_sel_hi:[0,1,1] neg_lo:[1,0,0] neg_hi:[1,0,0]
	v_pk_fma_f32 v[4:5], v[186:187], v[72:73], v[4:5] op_sel_hi:[0,1,1] neg_lo:[1,0,0] neg_hi:[1,0,0]
	v_pk_fma_f32 v[8:9], v[186:187], v[2:3], v[66:67] op_sel:[1,0,0]
	v_pk_fma_f32 v[2:3], v[186:187], v[0:1], v[64:65] op_sel:[1,0,0]
	v_pk_fma_f32 v[6:7], v[186:187], v[6:7], v[78:79] op_sel:[1,0,0]
	v_pk_fma_f32 v[4:5], v[186:187], v[4:5], v[76:77] op_sel:[1,0,0]
	s_nop 0
	v_cvt_pk_bf16_f32 v0, v4, v5
	v_cvt_pk_bf16_f32 v1, v6, v7
	v_cvt_pk_bf16_f32 v2, v2, v3
	v_cvt_pk_bf16_f32 v3, v8, v9
	global_store_dwordx4 v[84:85], v[0:3], off offset:256
	s_andn2_b64 vcc, exec, s[8:9]
	s_mov_b64 s[4:5], -1
	s_cbranch_vccnz .LBB0_726
